# Kfull table build moved from phase 4 into the idle tail of phase 2 (after the deferred transposes); phase 4 keeps only the ctx rows
# baseline (speedup 1.0000x reference)
; __device__ __forceinline__ bf16_t f2bf(float f) { return (bf16_t)(pk2(f, f) & 0xffffu); }
; __device__ __forceinline__ void phase4(const Params& P) {
;     ...
;     auto kf_val = [&](int e) -> float {
;         const int k = e & 511, n = (e >> 9) & 511, g = e >> 18;
;         const int t = n >> 4, c = n & 15, s = k >> 4, cp = k & 15;
;         const int d0 = t - s, d1 = s - t;
;         const float a0 = KD[(((0 * 32 + g) * 32 + (d0 > 0 ? d0 : 0)) * 16 + c) * 16 + cp];
;         const float a1 = KD[(((1 * 32 + g) * 32 + (d1 > 0 ? d1 : 0)) * 16 + c) * 16 + cp];
;         return (s <= t ? a0 : 0.f) + (s >= t ? a1 : 0.f);
;     };
;     auto kf_idx = [&](int e) -> size_t { const int k = e & 511, n = (e >> 9) & 511, g = e >> 18; return ((size_t)g * 512 + n) * 768 + k; };
;     {
;         constexpr int N = 32 * 512 * 512;
;         int e0 = gtid;
;         for (; e0 + 3 * gsz < N; e0 += 4 * gsz) {
;             float val[4];
; #pragma unroll
;             for (int q = 0; q < 4; ++q) val[q] = kf_val(e0 + q * gsz);
; #pragma unroll
;             for (int q = 0; q < 4; ++q) WY[kf_idx(e0 + q * gsz)] = f2bf(val[q]);
;         }
;         for (; e0 < N; e0 += gsz) WY[kf_idx(e0)] = f2bf(kf_val(e0));
.Ltq_pe5:
.Ltq_done:
	s_nop 0
	s_nop 0
	s_nop 0
	s_nop 0
	s_nop 0
	s_nop 0
	s_nop 0
	s_nop 0
	s_nop 0
	s_nop 0
	s_nop 0
	s_nop 0
	s_nop 0
	v_lshrrev_b32_e32 v0, 1, v170
	v_and_b32_e32 v1, 1, v170
	v_lshlrev_b32_e32 v2, 4, v170
	v_lshlrev_b32_e32 v1, 5, v1
	v_readfirstlane_b32 s0, v171
	s_nop 3
	s_sub_u32 s1, s33, 88
	s_lshl_b32 s1, s1, 3
	s_add_u32 s0, s0, s1
.Lkt_loop:
	s_lshr_b32 s10, s0, 9
	s_bfe_u32 s11, s0, 0x50004
	s_and_b32 s12, s0, 15
	s_lshl_b32 s10, s10, 15
	s_lshl_b32 s12, s12, 6
	s_add_u32 s10, s10, s12
	s_add_u32 s10, s10, 0x4e00000
	s_add_u32 s14, s68, s10
	s_addc_u32 s15, s69, 0
	s_add_u32 s16, s14, 0x100000
	s_addc_u32 s17, s15, 0
	v_sub_u32_e32 v8, s11, v0
	v_subrev_u32_e32 v9, s11, v0
	v_max_i32_e32 v8, 0, v8
	v_max_i32_e32 v9, 0, v9
	v_lshl_add_u32 v8, v8, 10, v1
	v_lshl_add_u32 v9, v9, 10, v1
	global_load_dwordx4 v[12:15], v8, s[14:15]
	global_load_dwordx4 v[16:19], v8, s[14:15] offset:16
	global_load_dwordx4 v[20:23], v9, s[16:17]
	global_load_dwordx4 v[24:27], v9, s[16:17] offset:16
	s_add_u32 s2, s0, 0x540
	s_cmpk_lt_u32 s2, 0x4000
	s_cbranch_scc0 .Lkt_oneA
	s_lshr_b32 s18, s2, 9
	s_bfe_u32 s19, s2, 0x50004
	s_and_b32 s20, s2, 15
	s_lshl_b32 s18, s18, 15
	s_lshl_b32 s20, s20, 6
	s_add_u32 s18, s18, s20
	s_add_u32 s18, s18, 0x4e00000
	s_add_u32 s22, s68, s18
	s_addc_u32 s23, s69, 0
	s_add_u32 s24, s22, 0x100000
	s_addc_u32 s25, s23, 0
	v_sub_u32_e32 v32, s19, v0
	v_subrev_u32_e32 v33, s19, v0
	v_max_i32_e32 v32, 0, v32
	v_max_i32_e32 v33, 0, v33
	v_lshl_add_u32 v32, v32, 10, v1
	v_lshl_add_u32 v33, v33, 10, v1
	global_load_dwordx4 v[36:39], v32, s[22:23]
	global_load_dwordx4 v[40:43], v32, s[22:23] offset:16
	global_load_dwordx4 v[44:47], v33, s[24:25]
	global_load_dwordx4 v[48:51], v33, s[24:25] offset:16
	s_mov_b32 s3, 1
	s_branch .Lkt_compute

; __device__ __forceinline__ bf16_t f2bf(float f) { return (bf16_t)(pk2(f, f) & 0xffffu); }
; __device__ __forceinline__ void phase4(const Params& P) {
;     ...
;     auto kf_val = [&](int e) -> float {
;         const int k = e & 511, n = (e >> 9) & 511, g = e >> 18;
;         const int t = n >> 4, c = n & 15, s = k >> 4, cp = k & 15;
;         const int d0 = t - s, d1 = s - t;
;         const float a0 = KD[(((0 * 32 + g) * 32 + (d0 > 0 ? d0 : 0)) * 16 + c) * 16 + cp];
;         const float a1 = KD[(((1 * 32 + g) * 32 + (d1 > 0 ? d1 : 0)) * 16 + c) * 16 + cp];
;         return (s <= t ? a0 : 0.f) + (s >= t ? a1 : 0.f);
;     };
;     auto kf_idx = [&](int e) -> size_t { const int k = e & 511, n = (e >> 9) & 511, g = e >> 18; return ((size_t)g * 512 + n) * 768 + k; };
;     {
;         constexpr int N = 32 * 512 * 512;
;         int e0 = gtid;
;         for (; e0 + 3 * gsz < N; e0 += 4 * gsz) {
;             float val[4];
; #pragma unroll
;             for (int q = 0; q < 4; ++q) val[q] = kf_val(e0 + q * gsz);
; #pragma unroll
;             for (int q = 0; q < 4; ++q) WY[kf_idx(e0 + q * gsz)] = f2bf(val[q]);
;         }
;         for (; e0 < N; e0 += gsz) WY[kf_idx(e0)] = f2bf(kf_val(e0));
; __device__ __forceinline__ void xcd_barrier(const XcdBarrier& b) {
;     asm volatile("s_waitcnt vmcnt(0)" ::: "memory");
;     __syncthreads();
;     if (threadIdx.x == 0) {
;         unsigned* bar = b.bar;
;         __builtin_amdgcn_s_waitcnt(0);
;         unsigned nloc = b.st[0], nx = b.st[1];
;         if (nloc == 0u) { xcd_barrier_complete(bar, b.x, nloc, nx); b.st[0] = nloc; b.st[1] = nx; }
.Lkt_compute:
	s_cmp_eq_u32 s3, 0
	s_cbranch_scc1 .Lkt_singleA
	s_waitcnt vmcnt(4)
	v_cmp_ge_u32_e32 vcc, s11, v0
	s_nop 1
	v_cndmask_b32_e32 v12, 0, v12, vcc
	v_cndmask_b32_e32 v13, 0, v13, vcc
	v_cndmask_b32_e32 v14, 0, v14, vcc
	v_cndmask_b32_e32 v15, 0, v15, vcc
	v_cndmask_b32_e32 v16, 0, v16, vcc
	v_cndmask_b32_e32 v17, 0, v17, vcc
	v_cndmask_b32_e32 v18, 0, v18, vcc
	v_cndmask_b32_e32 v19, 0, v19, vcc
	v_cmp_le_u32_e32 vcc, s11, v0
	s_nop 1
	v_cndmask_b32_e32 v20, 0, v20, vcc
	v_cndmask_b32_e32 v21, 0, v21, vcc
	v_cndmask_b32_e32 v22, 0, v22, vcc
	v_cndmask_b32_e32 v23, 0, v23, vcc
	v_cndmask_b32_e32 v24, 0, v24, vcc
	v_cndmask_b32_e32 v25, 0, v25, vcc
	v_cndmask_b32_e32 v26, 0, v26, vcc
	v_cndmask_b32_e32 v27, 0, v27, vcc
	v_add_f32_e32 v12, v12, v20
	v_add_f32_e32 v13, v13, v21
	v_add_f32_e32 v14, v14, v22
	v_add_f32_e32 v15, v15, v23
	v_add_f32_e32 v16, v16, v24
	v_add_f32_e32 v17, v17, v25
	v_add_f32_e32 v18, v18, v26
	v_add_f32_e32 v19, v19, v27
	v_cvt_pk_bf16_f32 v12, v12, v13
	v_cvt_pk_bf16_f32 v13, v14, v15
	v_cvt_pk_bf16_f32 v14, v16, v17
	v_cvt_pk_bf16_f32 v15, v18, v19
	s_mul_i32 s10, s0, 0x600
	s_add_u32 s14, s68, s10
	s_addc_u32 s15, s69, 0
	s_add_u32 s14, s14, 0x3600000
	s_addc_u32 s15, s15, 0
	global_store_dwordx4 v2, v[12:15], s[14:15]
	s_waitcnt vmcnt(1)
	v_cmp_ge_u32_e32 vcc, s19, v0
	s_nop 1
	v_cndmask_b32_e32 v36, 0, v36, vcc
	v_cndmask_b32_e32 v37, 0, v37, vcc
	v_cndmask_b32_e32 v38, 0, v38, vcc
	v_cndmask_b32_e32 v39, 0, v39, vcc
	v_cndmask_b32_e32 v40, 0, v40, vcc
	v_cndmask_b32_e32 v41, 0, v41, vcc
	v_cndmask_b32_e32 v42, 0, v42, vcc
	v_cndmask_b32_e32 v43, 0, v43, vcc
	v_cmp_le_u32_e32 vcc, s19, v0
	s_nop 1
	v_cndmask_b32_e32 v44, 0, v44, vcc
	v_cndmask_b32_e32 v45, 0, v45, vcc
	v_cndmask_b32_e32 v46, 0, v46, vcc
	v_cndmask_b32_e32 v47, 0, v47, vcc
	v_cndmask_b32_e32 v48, 0, v48, vcc
	v_cndmask_b32_e32 v49, 0, v49, vcc
	v_cndmask_b32_e32 v50, 0, v50, vcc
	v_cndmask_b32_e32 v51, 0, v51, vcc
	v_add_f32_e32 v36, v36, v44
	v_add_f32_e32 v37, v37, v45
	v_add_f32_e32 v38, v38, v46
	v_add_f32_e32 v39, v39, v47
	v_add_f32_e32 v40, v40, v48
	v_add_f32_e32 v41, v41, v49
	v_add_f32_e32 v42, v42, v50
	v_add_f32_e32 v43, v43, v51
	v_cvt_pk_bf16_f32 v36, v36, v37
	v_cvt_pk_bf16_f32 v37, v38, v39
	v_cvt_pk_bf16_f32 v38, v40, v41
	v_cvt_pk_bf16_f32 v39, v42, v43
	s_mul_i32 s18, s2, 0x600
	s_add_u32 s22, s68, s18
	s_addc_u32 s23, s69, 0
	s_add_u32 s22, s22, 0x3600000
	s_addc_u32 s23, s23, 0
	global_store_dwordx4 v2, v[36:39], s[22:23]
	s_add_u32 s0, s0, 0xa80
	s_cmpk_lt_u32 s0, 0x4000
	s_cbranch_scc1 .Lkt_loop
	s_branch .Lkt_done
.Lkt_singleA:
	s_waitcnt vmcnt(0)
	v_cmp_ge_u32_e32 vcc, s11, v0
	s_nop 1
	v_cndmask_b32_e32 v12, 0, v12, vcc
	v_cndmask_b32_e32 v13, 0, v13, vcc
	v_cndmask_b32_e32 v14, 0, v14, vcc
	v_cndmask_b32_e32 v15, 0, v15, vcc
	v_cndmask_b32_e32 v16, 0, v16, vcc
	v_cndmask_b32_e32 v17, 0, v17, vcc
	v_cndmask_b32_e32 v18, 0, v18, vcc
	v_cndmask_b32_e32 v19, 0, v19, vcc
	v_cmp_le_u32_e32 vcc, s11, v0
	s_nop 1
	v_cndmask_b32_e32 v20, 0, v20, vcc
	v_cndmask_b32_e32 v21, 0, v21, vcc
	v_cndmask_b32_e32 v22, 0, v22, vcc
	v_cndmask_b32_e32 v23, 0, v23, vcc
	v_cndmask_b32_e32 v24, 0, v24, vcc
	v_cndmask_b32_e32 v25, 0, v25, vcc
	v_cndmask_b32_e32 v26, 0, v26, vcc
	v_cndmask_b32_e32 v27, 0, v27, vcc
	v_add_f32_e32 v12, v12, v20
	v_add_f32_e32 v13, v13, v21
	v_add_f32_e32 v14, v14, v22
	v_add_f32_e32 v15, v15, v23
	v_add_f32_e32 v16, v16, v24
	v_add_f32_e32 v17, v17, v25
	v_add_f32_e32 v18, v18, v26
	v_add_f32_e32 v19, v19, v27
	v_cvt_pk_bf16_f32 v12, v12, v13
	v_cvt_pk_bf16_f32 v13, v14, v15
	v_cvt_pk_bf16_f32 v14, v16, v17
	v_cvt_pk_bf16_f32 v15, v18, v19
	s_mul_i32 s10, s0, 0x600
	s_add_u32 s14, s68, s10
	s_addc_u32 s15, s69, 0
	s_add_u32 s14, s14, 0x3600000
	s_addc_u32 s15, s15, 0
	global_store_dwordx4 v2, v[12:15], s[14:15]
.Lkt_done:
	s_nop 0
	s_nop 0
.Ltq_skip:
	s_cmp_lt_i32 s71, 4
	s_cbranch_scc1 .LBB0_332
	s_waitcnt vmcnt(0)
	s_waitcnt vmcnt(0) lgkmcnt(0)
	s_barrier
	s_mov_b64 s[0:1], exec
	v_readlane_b32 s2, v251, 3
	v_readlane_b32 s3, v251, 4
	s_and_b64 s[2:3], s[0:1], s[2:3]
	s_mov_b64 exec, s[2:3]
	s_cbranch_execz .LBB0_331
	v_mov_b32_e32 v0, 0
	s_waitcnt vmcnt(0) expcnt(0) lgkmcnt(0)
	ds_read_b32 v2, v0
	ds_read_b32 v1, v0 offset:4
	s_waitcnt lgkmcnt(1)
	v_cmp_ne_u32_e32 vcc, 0, v2
	s_cbranch_vccnz .LBB0_299
	v_readlane_b32 s2, v251, 0
	s_mul_i32 s48, s91, s2
	s_add_u32 s2, s68, 0x1ef3d200
	s_addc_u32 s3, s69, 0
	s_add_u32 s4, s68, 0x1ef3d400
	s_addc_u32 s5, s69, 0
	s_add_u32 s6, s68, 0x1ef3d500
	s_addc_u32 s7, s69, 0
	s_add_u32 s10, s68, 0x1ef3d600
	s_addc_u32 s11, s69, 0
	s_add_u32 s12, s68, 0x1ef3d700
	s_addc_u32 s13, s69, 0
	s_add_u32 s14, s68, 0x1ef3d800
	s_addc_u32 s15, s69, 0
	s_add_u32 s16, s68, 0x1ef3d900
	s_addc_u32 s17, s69, 0
	s_add_u32 s18, s68, 0x1ef3da00
	s_addc_u32 s19, s69, 0
	s_add_u32 s20, s68, 0x1ef3db00
	s_addc_u32 s21, s69, 0
	s_add_u32 s22, s68, 0x1ef3dc00
	s_addc_u32 s23, s69, 0
	s_add_u32 s24, s68, 0x1ef3dd00
	s_addc_u32 s25, s69, 0
	s_add_u32 s26, s68, 0x1ef3de00
	s_addc_u32 s27, s69, 0
	s_add_u32 s28, s68, 0x1ef3df00
	s_addc_u32 s29, s69, 0
	s_add_u32 s30, s68, 0x1ef3e000
	s_addc_u32 s31, s69, 0
	s_add_u32 s34, s68, 0x1ef3e100
	s_addc_u32 s35, s69, 0
	s_add_u32 s38, s68, 0x1ef3e200
	s_addc_u32 s39, s69, 0
	s_add_u32 s40, s68, 0x1ef3e300
	s_mul_i32 s48, s48, s90
	s_addc_u32 s41, s69, 0
	s_mov_b32 s49, 1
	s_branch .LBB0_287

; __device__ __forceinline__ bf16_t f2bf(float f) { return (bf16_t)(pk2(f, f) & 0xffffu); }
; __device__ __forceinline__ void phase4(const Params& P) {
;     ...
;     const bool split = gridDim.x > 64;
;     if (split && blockIdx.x < 32) return;
;     const int gtid = (split ? (int)blockIdx.x - 32 : (int)blockIdx.x) * NTHR + threadIdx.x, gsz = (split ? (int)gridDim.x - 32 : (int)gridDim.x) * NTHR;
;     const float* KD = (const float*)(P.ws + OFF_KD);
;     bf16_t* WY = (bf16_t*)(P.ws + OFF_WY);
;     auto kf_val = [&](int e) -> float {
;         const int k = e & 511, n = (e >> 9) & 511, g = e >> 18;
;         const int t = n >> 4, c = n & 15, s = k >> 4, cp = k & 15;
;         const int d0 = t - s, d1 = s - t;
;         const float a0 = KD[(((0 * 32 + g) * 32 + (d0 > 0 ? d0 : 0)) * 16 + c) * 16 + cp];
;         const float a1 = KD[(((1 * 32 + g) * 32 + (d1 > 0 ? d1 : 0)) * 16 + c) * 16 + cp];
;         return (s <= t ? a0 : 0.f) + (s >= t ? a1 : 0.f);
;     };
;     auto kf_idx = [&](int e) -> size_t { const int k = e & 511, n = (e >> 9) & 511, g = e >> 18; return ((size_t)g * 512 + n) * 768 + k; };
;     {
;         constexpr int N = 32 * 512 * 512;
;         int e0 = gtid;
;         for (; e0 + 3 * gsz < N; e0 += 4 * gsz) {
;             float val[4];
; #pragma unroll
;             for (int q = 0; q < 4; ++q) val[q] = kf_val(e0 + q * gsz);
; #pragma unroll
;             for (int q = 0; q < 4; ++q) WY[kf_idx(e0 + q * gsz)] = f2bf(val[q]);
;         }
;         for (; e0 < N; e0 += gsz) WY[kf_idx(e0)] = f2bf(kf_val(e0));
;     }
.LBB0_445:
	s_mov_b64 s[6:7], exec
	s_branch .LBB0_457
	s_nop 0
	s_nop 0
	s_nop 0
	s_nop 0
	s_nop 0
	s_nop 0
	s_nop 0
	s_nop 0
	s_nop 0
	s_nop 0
	s_nop 0
